# sample FOX cache stream: register double-buffering (2 tiles in flight), persistent regs saved to LDS around the q0 phase
# speedup vs baseline: 1.0141x; 1.0127x over previous
; #define LDS_AS __attribute__((address_space(3)))
;     ...
;     const float* ck = (MODE == 0 ? p.cak : p.cbk) + (size_t)bb * PAST * 512;
;     const float* cv = (MODE == 0 ? p.cav : p.cbv) + (size_t)bb * PAST * 512;
;     const int ntc = (MODE == 1 ? (PAST / NSPLIT / 32) : 128), kbase = (MODE == 1 ? (PAST / NSPLIT) * split : 0);
;     const bool has_new = (MODE == 0) || (split == NSPLIT - 1);
;     const float* cseq = p.c2s + (size_t)(bb * 8 + ((tid >> 5) & 7)) * LSK;
;     float cref = 0.f;
;     if (MODE == 1 && tid < 256) cref = cseq[PAST];
;     constexpr int KOFF = 0, VOFF = 36864, BOFF = 73728, HSTR = 4608;
;     bool wdone = false, alldone = false;
;     if (has_new) {
;         __syncthreads();
;         const bf16_t* kb = p.u + ((size_t)ROWS_P + bb * 32) * NU + segb + 512;
; #pragma unroll
;         for (int i = 0; i < 4; ++i) {
;             const int id = tid + 512 * i, r = id >> 6, c = id & 63, hd = c >> 3, d = (c & 7) * 8;
;             const u32x4 kx = *(const u32x4*)(kb + (size_t)r * NU + c * 8);
;             const u32x4 vx = *(const u32x4*)(kb + (size_t)r * NU + 512 + c * 8);
;             *(LDS_AS u32x4*)(lb + KOFF + hd * HSTR + r * 144 + d * 2) = kx;
;             *(LDS_AS u32x4*)(lb + VOFF + hd * HSTR + r * 144 + d * 2) = vx;
;         }
;         if (MODE == 1 && tid < 256) *(LDS_AS float*)(lb + BOFF + tid * 4) = cref - cseq[PAST + (tid & 31)];
;         __syncthreads();
;         attn_subtile<MODE>(lb + KOFF + wave * HSTR, lb + VOFF + wave * HSTR, lb + BOFF + wave * 128, q, st, PAST, qpos, true, lane);
;         if (MODE == 0) { wdone = __all(st.l < -SB_THRESH); alldone = __syncthreads_and(wdone ? 1 : 0) != 0; }
;     }
;     if (!alldone) {
;         f32x4 tk[8], tv[8]; float tb = 0.f;
;         const int rot = (MODE == 1) ? ((bb * NSPLIT + split) * 5) % ntc : 0;
;         {
;             const int t0i = (ntc - 1 + rot) % ntc;
;             const float* kg = ck + (size_t)(kbase + 32 * t0i) * 512;
;             const float* vg = cv + (size_t)(kbase + 32 * t0i) * 512;
;             if (MODE == 1 && tid < 256) tb = cseq[kbase + 32 * t0i + (tid & 31)];
; #pragma unroll
;             for (int i = 0; i < 8; ++i) { const int id = tid + 512 * i; tk[i] = __builtin_nontemporal_load((const f32x4*)(kg + (size_t)id * 4)); tv[i] = __builtin_nontemporal_load((const f32x4*)(vg + (size_t)id * 4)); }
;         }
.LBB0_455:
	s_or_b64 exec, exec, s[34:35]
	s_ashr_i32 s7, s6, 31
	s_lshl_b64 s[34:35], s[6:7], 23
	s_add_u32 s36, s84, s34
	s_addc_u32 s37, s85, s35
	s_add_u32 s38, s86, s34
	s_addc_u32 s39, s87, s35
	s_ashr_i32 s31, s30, 31
	s_lshl_b64 s[30:31], s[30:31], 11
	s_add_u32 s34, s36, s30
	s_addc_u32 s35, s37, s31
	s_add_u32 s30, s38, s30
	v_ashrrev_i32_e32 v135, 31, v134
	s_addc_u32 s31, s39, s31
	v_lshlrev_b64 v[40:41], 4, v[134:135]
	v_lshl_add_u64 v[42:43], s[34:35], 0, v[40:41]
	v_lshl_add_u64 v[40:41], s[30:31], 0, v[40:41]
	v_ashrrev_i32_e32 v37, 31, v36
	global_load_dwordx4 v[68:71], v[40:41], off nt
	v_lshlrev_b64 v[40:41], 4, v[36:37]
	global_load_dwordx4 v[64:67], v[42:43], off nt
	v_lshl_add_u64 v[42:43], s[34:35], 0, v[40:41]
	v_lshl_add_u64 v[40:41], s[30:31], 0, v[40:41]
	v_ashrrev_i32_e32 v35, 31, v34
	global_load_dwordx4 v[76:79], v[40:41], off nt
	v_lshlrev_b64 v[40:41], 4, v[34:35]
	global_load_dwordx4 v[72:75], v[42:43], off nt
	v_lshl_add_u64 v[42:43], s[34:35], 0, v[40:41]
	v_lshl_add_u64 v[40:41], s[30:31], 0, v[40:41]
	v_ashrrev_i32_e32 v33, 31, v32
	global_load_dwordx4 v[84:87], v[40:41], off nt
	v_lshlrev_b64 v[40:41], 4, v[32:33]
	global_load_dwordx4 v[80:83], v[42:43], off nt
	v_lshl_add_u64 v[42:43], s[34:35], 0, v[40:41]
	v_lshl_add_u64 v[40:41], s[30:31], 0, v[40:41]
	global_load_dwordx4 v[92:95], v[40:41], off nt
	v_add_u32_e32 v40, 0x800, v134
	v_ashrrev_i32_e32 v41, 31, v40
	global_load_dwordx4 v[88:91], v[42:43], off nt
	v_lshlrev_b64 v[42:43], 4, v[40:41]
	v_lshl_add_u64 v[44:45], s[34:35], 0, v[42:43]
	v_lshl_add_u64 v[42:43], s[30:31], 0, v[42:43]
	global_load_dwordx4 v[100:103], v[42:43], off nt
	v_add_u32_e32 v42, 0xa00, v134
	v_ashrrev_i32_e32 v43, 31, v42
	global_load_dwordx4 v[96:99], v[44:45], off nt
	v_lshlrev_b64 v[44:45], 4, v[42:43]
	v_lshl_add_u64 v[46:47], s[34:35], 0, v[44:45]
	v_lshl_add_u64 v[44:45], s[30:31], 0, v[44:45]
	global_load_dwordx4 v[108:111], v[44:45], off nt
	v_add_u32_e32 v44, 0xc00, v134
	v_ashrrev_i32_e32 v45, 31, v44
	global_load_dwordx4 v[104:107], v[46:47], off nt
	v_lshlrev_b64 v[46:47], 4, v[44:45]
	s_waitcnt vmcnt(27)
	v_lshl_add_u64 v[112:113], s[34:35], 0, v[46:47]
	v_lshl_add_u64 v[46:47], s[30:31], 0, v[46:47]
	global_load_dwordx4 v[116:119], v[46:47], off nt
	v_add_u32_e32 v46, 0xe00, v134
	v_ashrrev_i32_e32 v47, 31, v46
	s_waitcnt vmcnt(25)
	v_lshlrev_b64 v[124:125], 4, v[46:47]
	v_lshl_add_u64 v[120:121], s[34:35], 0, v[124:125]
	v_lshl_add_u64 v[124:125], s[30:31], 0, v[124:125]
	global_load_dwordx4 v[112:115], v[112:113], off nt
	v_lshlrev_b64 v[160:161], 2, v[42:43]
	global_load_dwordx4 v[120:123], v[120:121], off nt
	v_and_b32_e32 v43, 64, v174
	global_load_dwordx4 v[124:127], v[124:125], off nt
	v_lshlrev_b64 v[158:159], 2, v[40:41]
	v_xor_b32_e32 v41, 32, v174
	v_add_u32_e32 v43, 64, v43
	v_cmp_lt_i32_e32 vcc, v41, v43
	v_lshlrev_b64 v[154:155], 2, v[34:35]
	v_lshlrev_b64 v[156:157], 2, v[32:33]
	v_bfe_u32 v33, v134, 4, 3
	v_lshlrev_b32_e32 v35, 3, v134
	v_cndmask_b32_e32 v41, v174, v41, vcc
	v_lshlrev_b64 v[150:151], 2, v[134:135]
	v_and_b32_e32 v35, 0x78, v35
	v_mul_u32_u24_e32 v33, 0x1200, v33
	v_lshlrev_b32_e32 v181, 2, v41
	v_lshrrev_b32_e32 v41, 2, v134
	v_lshlrev_b32_e32 v135, 2, v38
	v_add3_u32 v33, s62, v33, v35
	v_mul_lo_u32 v35, v136, s91
	v_and_b32_e32 v43, 16, v134
	v_and_or_b32 v38, v41, 3, v135
	v_lshlrev_b32_e32 v41, 2, v133
	v_add_u32_e32 v35, 0x100, v35
	v_and_or_b32 v41, v41, 12, v43
	v_ashrrev_i32_e32 v32, 7, v32
	v_lshlrev_b64 v[152:153], 2, v[36:37]
	v_lshlrev_b64 v[162:163], 2, v[44:45]
	s_add_i32 s30, s92, 0x100
	v_mad_u32_u24 v39, v176, s89, v35
	v_mad_u32_u24 v35, v38, s89, v35
	v_lshlrev_b32_e32 v38, 1, v41
	v_lshlrev_b32_e32 v41, 2, v134
	v_ashrrev_i32_e32 v43, 7, v134
	v_ashrrev_i32_e32 v36, 7, v36
	v_ashrrev_i32_e32 v34, 7, v34
	v_mul_lo_u32 v32, v32, s89
	v_ashrrev_i32_e32 v40, 7, v40
	v_ashrrev_i32_e32 v42, 7, v42
	v_ashrrev_i32_e32 v44, 7, v44
	v_ashrrev_i32_e32 v45, 7, v46
	v_lshlrev_b64 v[164:165], 2, v[46:47]
	v_lshl_add_u32 v37, v136, 7, s30
	v_mul_lo_u32 v43, v43, s89
	v_mul_lo_u32 v36, v36, s89
	v_mul_lo_u32 v34, v34, s89
	v_mul_lo_u32 v40, v40, s89
	v_mul_lo_u32 v42, v42, s89
	v_mul_lo_u32 v44, v44, s89
	v_mul_lo_u32 v45, v45, s89
	v_add_u32_e32 v185, v33, v32
	v_add_u32_e32 v32, 0x100, v41
	s_movk_i32 s42, 0x7c0
	v_add_u32_e32 v182, v33, v43
	v_add_u32_e32 v183, v33, v36
	v_add_u32_e32 v184, v33, v34
	v_add_u32_e32 v186, v33, v40
	v_add_u32_e32 v187, v33, v42
	v_add_u32_e32 v188, v33, v44
	v_add_u32_e32 v189, v33, v45
	v_add_u32_e32 v190, 0x12000, v32
	v_lshlrev_b64 v[150:151], 2, v[150:151]
	v_lshlrev_b64 v[152:153], 2, v[152:153]
	v_lshlrev_b64 v[154:155], 2, v[154:155]
	v_lshlrev_b64 v[156:157], 2, v[156:157]
	v_lshlrev_b64 v[158:159], 2, v[158:159]
	v_lshlrev_b64 v[160:161], 2, v[160:161]
	v_lshlrev_b64 v[162:163], 2, v[162:163]
	v_lshlrev_b64 v[164:165], 2, v[164:165]
	v_add_u32_e32 v191, v37, v130
	v_add_u32_e32 v130, v39, v130
	v_add_u32_e32 v192, v35, v38
	s_add_i32 s30, s10, s42
	s_and_b32 s30, s30, 0x3e0
	s_or_b32 s30, s30, s9
	s_and_saveexec_b64 s[34:35], s[0:1]
	s_cbranch_execz .Lss_p461
	v_or_b32_e32 v32, s30, v176
	v_ashrrev_i32_e32 v33, 31, v32
	v_lshl_add_u64 v[32:33], v[32:33], 2, v[148:149]
	global_load_dword v144, v[32:33], off
; #define LDS_AS __attribute__((address_space(3)))
; DI unsigned pk2(float a, float b) { f32x2 v = {a, b}; bf16x2v r = __builtin_convertvector(v, bf16x2v); return __builtin_bit_cast(unsigned, r); }
;     ...
;             const int kpos0 = kbase + 32 * ((it + rot) % ntc);
;             const int kposn = kbase + 32 * ((it - 1 + rot + ntc) % ntc);
;             __syncthreads();
; #pragma unroll
;             for (int i = 0; i < 8; ++i) {
;                 const int id = tid + 512 * i, r = id >> 7, c4 = id & 127, hd = c4 >> 4, d = (c4 & 15) * 4;
;                 *(LDS_AS u32x2*)(lb + KOFF + hd * HSTR + r * 144 + d * 2) = (u32x2){pk2(tk[i][0], tk[i][1]), pk2(tk[i][2], tk[i][3])};
;                 *(LDS_AS u32x2*)(lb + VOFF + hd * HSTR + r * 144 + d * 2) = (u32x2){pk2(tv[i][0], tv[i][1]), pk2(tv[i][2], tv[i][3])};
;             }
;             if (MODE == 1 && tid < 256) *(LDS_AS float*)(lb + BOFF + tid * 4) = cref - tb;
;             if (it > 0) {
;                 const float* kg = ck + (size_t)kposn * 512;
;                 const float* vg = cv + (size_t)kposn * 512;
;                 if (MODE == 1 && tid < 256) tb = cseq[kposn + (tid & 31)];
; #pragma unroll
;                 for (int i = 0; i < 8; ++i) { const int id = tid + 512 * i; tk[i] = __builtin_nontemporal_load((const f32x4*)(kg + (size_t)id * 4)); tv[i] = __builtin_nontemporal_load((const f32x4*)(vg + (size_t)id * 4)); }
;             }
.Lss_p461:
	s_or_b64 exec, exec, s[34:35]
	s_ashr_i32 s31, s30, 31
	s_lshl_b64 s[30:31], s[30:31], 11
	s_add_u32 s34, s36, s30
	s_addc_u32 s35, s37, s31
	s_add_u32 s30, s38, s30
	s_addc_u32 s31, s39, s31
	v_lshl_add_u64 v[32:33], s[34:35], 0, v[150:151]
	global_load_dwordx4 v[204:207], v[32:33], off nt
	v_lshl_add_u64 v[32:33], s[30:31], 0, v[150:151]
	global_load_dwordx4 v[208:211], v[32:33], off nt
	v_lshl_add_u64 v[32:33], s[34:35], 0, v[152:153]
	global_load_dwordx4 v[212:215], v[32:33], off nt
	v_lshl_add_u64 v[32:33], s[30:31], 0, v[152:153]
	global_load_dwordx4 v[216:219], v[32:33], off nt
	v_lshl_add_u64 v[32:33], s[34:35], 0, v[154:155]
	global_load_dwordx4 v[220:223], v[32:33], off nt
	v_lshl_add_u64 v[32:33], s[30:31], 0, v[154:155]
	global_load_dwordx4 v[224:227], v[32:33], off nt
	v_lshl_add_u64 v[32:33], s[34:35], 0, v[156:157]
	global_load_dwordx4 v[228:231], v[32:33], off nt
	v_lshl_add_u64 v[32:33], s[30:31], 0, v[156:157]
	global_load_dwordx4 v[232:235], v[32:33], off nt
	v_lshl_add_u64 v[32:33], s[34:35], 0, v[158:159]
	global_load_dwordx4 v[236:239], v[32:33], off nt
	v_lshl_add_u64 v[32:33], s[30:31], 0, v[158:159]
	global_load_dwordx4 v[240:243], v[32:33], off nt
	v_lshl_add_u64 v[32:33], s[34:35], 0, v[160:161]
	global_load_dwordx4 v[244:247], v[32:33], off nt
	v_lshl_add_u64 v[32:33], s[30:31], 0, v[160:161]
	global_load_dwordx4 v[248:251], v[32:33], off nt
	v_lshl_add_u64 v[32:33], s[34:35], 0, v[162:163]
	global_load_dwordx4 v[252:255], v[32:33], off nt
	v_lshl_add_u64 v[32:33], s[30:31], 0, v[162:163]
	global_load_dwordx4 v[140:143], v[32:33], off nt
	v_lshl_add_u64 v[32:33], s[34:35], 0, v[164:165]
	global_load_dwordx4 v[166:169], v[32:33], off nt
	v_lshl_add_u64 v[32:33], s[30:31], 0, v[164:165]
	global_load_dwordx4 v[170:173], v[32:33], off nt
.LBB0_456:
	s_waitcnt vmcnt(30)
	v_cvt_pk_bf16_f32 v32, v64, v65
	v_cvt_pk_bf16_f32 v33, v66, v67
	v_cvt_pk_bf16_f32 v34, v68, v69
	v_cvt_pk_bf16_f32 v35, v70, v71
	s_barrier
	ds_write2st64_b64 v182, v[32:33], v[34:35] offset1:72
	s_waitcnt vmcnt(28)
	v_cvt_pk_bf16_f32 v32, v72, v73
	v_cvt_pk_bf16_f32 v33, v74, v75
	v_cvt_pk_bf16_f32 v34, v76, v77
	v_cvt_pk_bf16_f32 v35, v78, v79
	ds_write2st64_b64 v183, v[32:33], v[34:35] offset1:72
	s_waitcnt vmcnt(26)
	v_cvt_pk_bf16_f32 v32, v80, v81
	v_cvt_pk_bf16_f32 v33, v82, v83
	v_cvt_pk_bf16_f32 v34, v84, v85
	v_cvt_pk_bf16_f32 v35, v86, v87
	ds_write2st64_b64 v184, v[32:33], v[34:35] offset1:72
	s_waitcnt vmcnt(24)
	v_cvt_pk_bf16_f32 v32, v88, v89
	v_cvt_pk_bf16_f32 v33, v90, v91
	v_cvt_pk_bf16_f32 v34, v92, v93
	v_cvt_pk_bf16_f32 v35, v94, v95
	ds_write2st64_b64 v185, v[32:33], v[34:35] offset1:72
	s_waitcnt vmcnt(22)
	v_cvt_pk_bf16_f32 v32, v96, v97
	v_cvt_pk_bf16_f32 v33, v98, v99
	v_cvt_pk_bf16_f32 v34, v100, v101
	v_cvt_pk_bf16_f32 v35, v102, v103
	ds_write2st64_b64 v186, v[32:33], v[34:35] offset1:72
	s_waitcnt vmcnt(20)
	v_cvt_pk_bf16_f32 v32, v104, v105
	v_cvt_pk_bf16_f32 v33, v106, v107
	v_cvt_pk_bf16_f32 v34, v108, v109
	v_cvt_pk_bf16_f32 v35, v110, v111
	ds_write2st64_b64 v187, v[32:33], v[34:35] offset1:72
	s_waitcnt vmcnt(18)
	v_cvt_pk_bf16_f32 v32, v112, v113
	v_cvt_pk_bf16_f32 v33, v114, v115
	v_cvt_pk_bf16_f32 v34, v116, v117
	v_cvt_pk_bf16_f32 v35, v118, v119
	ds_write2st64_b64 v188, v[32:33], v[34:35] offset1:72
	s_waitcnt vmcnt(17)
	v_cvt_pk_bf16_f32 v32, v120, v121
	v_cvt_pk_bf16_f32 v33, v122, v123
	s_waitcnt vmcnt(16)
	v_cvt_pk_bf16_f32 v34, v124, v125
	v_cvt_pk_bf16_f32 v35, v126, v127
	ds_write2st64_b64 v189, v[32:33], v[34:35] offset1:72
	s_and_saveexec_b64 s[30:31], s[0:1]
	v_sub_f32_e32 v32, v177, v179
	ds_write_b32 v190, v32
	s_or_b64 exec, exec, s[30:31]
	s_cmpk_lt_u32 s42, 0x420
	s_cbranch_scc1 .Lss_a462
	s_add_i32 s30, s10, s42
	s_sub_i32 s30, s30, 32
	s_and_b32 s30, s30, 0x3e0
	s_or_b32 s30, s30, s9
	s_and_saveexec_b64 s[34:35], s[0:1]
	s_cbranch_execz .Lss_a461
	v_or_b32_e32 v32, s30, v176
	v_ashrrev_i32_e32 v33, 31, v32
	v_lshl_add_u64 v[32:33], v[32:33], 2, v[148:149]
	global_load_dword v179, v[32:33], off

; #define LDS_AS __attribute__((address_space(3)))
; DI unsigned pk2(float a, float b) { f32x2 v = {a, b}; bf16x2v r = __builtin_convertvector(v, bf16x2v); return __builtin_bit_cast(unsigned, r); }
; DI void fox_softmax32(f32x16& s, AttnState& st, bf16x8 (&pf)[2]) {
;     ...
;     for (int i = 0; i < 16; i += 2) {
;         f32x2 t = {s[i], s[i + 1]};
;         t = t - mn2;
;         t[0] = __builtin_amdgcn_exp2f(t[0]); t[1] = __builtin_amdgcn_exp2f(t[1]);
;         acc2 = acc2 + t;
;         s[i] = t[0]; s[i + 1] = t[1];
;     }
;     st.l += acc2[0] + acc2[1];
; #pragma unroll
;     for (int s2 = 0; s2 < 2; ++s2) {
;         u32x4 w;
;         w[0] = pk2(s[8 * s2 + 0], s[8 * s2 + 1]); w[1] = pk2(s[8 * s2 + 2], s[8 * s2 + 3]); w[2] = pk2(s[8 * s2 + 4], s[8 * s2 + 5]); w[3] = pk2(s[8 * s2 + 6], s[8 * s2 + 7]);
;         pf[s2] = __builtin_bit_cast(bf16x8, w);
;     }
;     ...
; #pragma unroll
;             for (int i = 0; i < 8; ++i) {
;                 const int id = tid + 512 * i, r = id >> 7, c4 = id & 127, hd = c4 >> 4, d = (c4 & 15) * 4;
;                 *(LDS_AS u32x2*)(lb + KOFF + hd * HSTR + r * 144 + d * 2) = (u32x2){pk2(tk[i][0], tk[i][1]), pk2(tk[i][2], tk[i][3])};
;                 *(LDS_AS u32x2*)(lb + VOFF + hd * HSTR + r * 144 + d * 2) = (u32x2){pk2(tv[i][0], tv[i][1]), pk2(tv[i][2], tv[i][3])};
;             }
;             if (MODE == 1 && tid < 256) *(LDS_AS float*)(lb + BOFF + tid * 4) = cref - tb;
;             if (it > 0) {
;                 const float* kg = ck + (size_t)kposn * 512;
;                 const float* vg = cv + (size_t)kposn * 512;
;                 if (MODE == 1 && tid < 256) tb = cseq[kposn + (tid & 31)];
; #pragma unroll
;                 for (int i = 0; i < 8; ++i) { const int id = tid + 512 * i; tk[i] = __builtin_nontemporal_load((const f32x4*)(kg + (size_t)id * 4)); tv[i] = __builtin_nontemporal_load((const f32x4*)(vg + (size_t)id * 4)); }
;             }
;             __builtin_amdgcn_sched_barrier(0);
;             __syncthreads();
;             if (!wdone) {
;                 attn_subtile<MODE>(lb + KOFF + wave * HSTR, lb + VOFF + wave * HSTR, lb + BOFF + wave * 128, q, st, kpos0, qpos, false, lane);
.Lss_a464:
	v_sub_f32_e32 v32, v32, v193
	v_exp_f32_e32 v180, v32
	v_sub_f32_e32 v32, v33, v193
	v_exp_f32_e32 v194, v32
	v_sub_f32_e32 v32, v34, v193
	v_exp_f32_e32 v195, v32
	v_sub_f32_e32 v32, v35, v193
	v_exp_f32_e32 v196, v32
	v_sub_f32_e32 v33, v36, v193
	v_add_f32_e32 v32, 0, v180
	v_exp_f32_e32 v197, v33
	v_sub_f32_e32 v33, v37, v193
	v_add_f32_e32 v32, v194, v32
	v_exp_f32_e32 v198, v33
	v_sub_f32_e32 v33, v38, v193
	v_add_f32_e32 v32, v195, v32
	v_exp_f32_e32 v199, v33
	v_sub_f32_e32 v33, v39, v193
	v_add_f32_e32 v32, v196, v32
	v_exp_f32_e32 v39, v33
	v_sub_f32_e32 v33, v40, v193
	v_add_f32_e32 v32, v197, v32
	v_exp_f32_e32 v200, v33
	v_sub_f32_e32 v33, v41, v193
	v_add_f32_e32 v32, v198, v32
	v_exp_f32_e32 v201, v33
	v_sub_f32_e32 v33, v42, v193
	v_add_f32_e32 v32, v199, v32
	v_exp_f32_e32 v202, v33
	v_sub_f32_e32 v33, v43, v193
	v_add_f32_e32 v32, v39, v32
	v_exp_f32_e32 v203, v33
	v_add_f32_e32 v32, v200, v32
	v_add_f32_e32 v32, v201, v32
	v_add_f32_e32 v32, v202, v32
	v_add_f32_e32 v146, v203, v32
	ds_read_b64_tr_b16 v[32:33], v192 offset:36864
	ds_read_b64_tr_b16 v[34:35], v192 offset:38016
	ds_read_b64_tr_b16 v[42:43], v192 offset:38080
	ds_read_b64_tr_b16 v[40:41], v192 offset:36928
	v_sub_f32_e32 v36, v44, v193
	v_exp_f32_e32 v44, v36
	v_cvt_pk_bf16_f32 v36, v180, v194
	v_cvt_pk_bf16_f32 v37, v195, v196
	v_cvt_pk_bf16_f32 v38, v197, v198
	v_cvt_pk_bf16_f32 v39, v199, v39
	v_sub_f32_e32 v47, v47, v193
	v_exp_f32_e32 v47, v47
	s_waitcnt lgkmcnt(2)
	v_mfma_f32_32x32x16_bf16 v[16:31], v[32:35], v[36:39], v[16:31]
	v_sub_f32_e32 v32, v45, v193
	v_exp_f32_e32 v45, v32
	v_sub_f32_e32 v32, v46, v193
	v_exp_f32_e32 v46, v32
	ds_read_b64_tr_b16 v[32:33], v192 offset:39168
	ds_read_b64_tr_b16 v[34:35], v192 offset:40320
	s_sub_i32 s42, s42, 32
	s_cmpk_eq_i32 s42, 0x3c0
	s_waitcnt lgkmcnt(2)
	v_mfma_f32_32x32x16_bf16 v[0:15], v[40:43], v[36:39], v[0:15]
	ds_read_b64_tr_b16 v[42:43], v192 offset:40384
	ds_read_b64_tr_b16 v[40:41], v192 offset:39232
	v_cvt_pk_bf16_f32 v36, v200, v201
	v_cvt_pk_bf16_f32 v37, v202, v203
	v_cvt_pk_bf16_f32 v38, v44, v45
	v_cvt_pk_bf16_f32 v39, v46, v47
	s_waitcnt lgkmcnt(2)
	s_nop 0
	v_mfma_f32_32x32x16_bf16 v[16:31], v[32:35], v[36:39], v[16:31]
	v_add_f32_e32 v32, v44, v146
	v_add_f32_e32 v32, v45, v32
	v_add_f32_e32 v32, v46, v32
	v_add_f32_e32 v32, v47, v32
	v_add_f32_e32 v178, v32, v178
	s_waitcnt lgkmcnt(0)
	v_mfma_f32_32x32x16_bf16 v[0:15], v[40:43], v[36:39], v[0:15]
	v_mov_b32_e32 v180, v193
	s_cmpk_eq_i32 s42, 0x3e0
	s_cbranch_scc1 .Lss_blast
	s_waitcnt vmcnt(30)
	v_cvt_pk_bf16_f32 v32, v204, v205
	v_cvt_pk_bf16_f32 v33, v206, v207
	v_cvt_pk_bf16_f32 v34, v208, v209
	v_cvt_pk_bf16_f32 v35, v210, v211
	s_barrier
	ds_write2st64_b64 v182, v[32:33], v[34:35] offset1:72
	s_waitcnt vmcnt(28)
	v_cvt_pk_bf16_f32 v32, v212, v213
	v_cvt_pk_bf16_f32 v33, v214, v215
	v_cvt_pk_bf16_f32 v34, v216, v217
	v_cvt_pk_bf16_f32 v35, v218, v219
	ds_write2st64_b64 v183, v[32:33], v[34:35] offset1:72
	s_waitcnt vmcnt(26)
	v_cvt_pk_bf16_f32 v32, v220, v221
	v_cvt_pk_bf16_f32 v33, v222, v223
	v_cvt_pk_bf16_f32 v34, v224, v225
	v_cvt_pk_bf16_f32 v35, v226, v227
	ds_write2st64_b64 v184, v[32:33], v[34:35] offset1:72
	s_waitcnt vmcnt(24)
	v_cvt_pk_bf16_f32 v32, v228, v229
	v_cvt_pk_bf16_f32 v33, v230, v231
	v_cvt_pk_bf16_f32 v34, v232, v233
	v_cvt_pk_bf16_f32 v35, v234, v235
	ds_write2st64_b64 v185, v[32:33], v[34:35] offset1:72
	s_waitcnt vmcnt(22)
	v_cvt_pk_bf16_f32 v32, v236, v237
	v_cvt_pk_bf16_f32 v33, v238, v239
	v_cvt_pk_bf16_f32 v34, v240, v241
	v_cvt_pk_bf16_f32 v35, v242, v243
	ds_write2st64_b64 v186, v[32:33], v[34:35] offset1:72
	s_waitcnt vmcnt(20)
	v_cvt_pk_bf16_f32 v32, v244, v245
	v_cvt_pk_bf16_f32 v33, v246, v247
	v_cvt_pk_bf16_f32 v34, v248, v249
	v_cvt_pk_bf16_f32 v35, v250, v251
	ds_write2st64_b64 v187, v[32:33], v[34:35] offset1:72
	s_waitcnt vmcnt(18)
	v_cvt_pk_bf16_f32 v32, v252, v253
	v_cvt_pk_bf16_f32 v33, v254, v255
	v_cvt_pk_bf16_f32 v34, v140, v141
	v_cvt_pk_bf16_f32 v35, v142, v143
	ds_write2st64_b64 v188, v[32:33], v[34:35] offset1:72
	s_waitcnt vmcnt(17)
	v_cvt_pk_bf16_f32 v32, v166, v167
	v_cvt_pk_bf16_f32 v33, v168, v169
	s_waitcnt vmcnt(16)
	v_cvt_pk_bf16_f32 v34, v170, v171
	v_cvt_pk_bf16_f32 v35, v172, v173
	ds_write2st64_b64 v189, v[32:33], v[34:35] offset1:72
	s_branch .Lss_bw
.Lss_blast:
	s_waitcnt vmcnt(14)
	v_cvt_pk_bf16_f32 v32, v204, v205
	v_cvt_pk_bf16_f32 v33, v206, v207
	v_cvt_pk_bf16_f32 v34, v208, v209
	v_cvt_pk_bf16_f32 v35, v210, v211
	s_barrier
	ds_write2st64_b64 v182, v[32:33], v[34:35] offset1:72
	s_waitcnt vmcnt(12)
	v_cvt_pk_bf16_f32 v32, v212, v213
	v_cvt_pk_bf16_f32 v33, v214, v215
	v_cvt_pk_bf16_f32 v34, v216, v217
	v_cvt_pk_bf16_f32 v35, v218, v219
	ds_write2st64_b64 v183, v[32:33], v[34:35] offset1:72
	s_waitcnt vmcnt(10)
	v_cvt_pk_bf16_f32 v32, v220, v221
	v_cvt_pk_bf16_f32 v33, v222, v223
	v_cvt_pk_bf16_f32 v34, v224, v225
	v_cvt_pk_bf16_f32 v35, v226, v227
	ds_write2st64_b64 v184, v[32:33], v[34:35] offset1:72
	s_waitcnt vmcnt(8)
	v_cvt_pk_bf16_f32 v32, v228, v229
	v_cvt_pk_bf16_f32 v33, v230, v231
	v_cvt_pk_bf16_f32 v34, v232, v233
	v_cvt_pk_bf16_f32 v35, v234, v235
	ds_write2st64_b64 v185, v[32:33], v[34:35] offset1:72
	s_waitcnt vmcnt(6)
	v_cvt_pk_bf16_f32 v32, v236, v237
	v_cvt_pk_bf16_f32 v33, v238, v239
	v_cvt_pk_bf16_f32 v34, v240, v241
	v_cvt_pk_bf16_f32 v35, v242, v243
	ds_write2st64_b64 v186, v[32:33], v[34:35] offset1:72
	s_waitcnt vmcnt(4)
	v_cvt_pk_bf16_f32 v32, v244, v245
	v_cvt_pk_bf16_f32 v33, v246, v247
	v_cvt_pk_bf16_f32 v34, v248, v249
	v_cvt_pk_bf16_f32 v35, v250, v251
	ds_write2st64_b64 v187, v[32:33], v[34:35] offset1:72
	s_waitcnt vmcnt(2)
	v_cvt_pk_bf16_f32 v32, v252, v253
	v_cvt_pk_bf16_f32 v33, v254, v255
	v_cvt_pk_bf16_f32 v34, v140, v141
	v_cvt_pk_bf16_f32 v35, v142, v143
	ds_write2st64_b64 v188, v[32:33], v[34:35] offset1:72
	s_waitcnt vmcnt(1)
	v_cvt_pk_bf16_f32 v32, v166, v167
	v_cvt_pk_bf16_f32 v33, v168, v169
	s_waitcnt vmcnt(0)
	v_cvt_pk_bf16_f32 v34, v170, v171
	v_cvt_pk_bf16_f32 v35, v172, v173
	ds_write2st64_b64 v189, v[32:33], v[34:35] offset1:72
.Lss_bw:
	s_and_saveexec_b64 s[30:31], s[0:1]
	v_sub_f32_e32 v32, v177, v144
	ds_write_b32 v190, v32
	s_or_b64 exec, exec, s[30:31]
	s_cmpk_lt_u32 s42, 0x420
	s_cbranch_scc1 .Lss_b462
	s_add_i32 s30, s10, s42
	s_sub_i32 s30, s30, 32
	s_and_b32 s30, s30, 0x3e0
	s_or_b32 s30, s30, s9
	s_and_saveexec_b64 s[34:35], s[0:1]
	s_cbranch_execz .Lss_b461
	v_or_b32_e32 v32, s30, v176
	v_ashrrev_i32_e32 v33, 31, v32
	v_lshl_add_u64 v[32:33], v[32:33], 2, v[148:149]
	global_load_dword v144, v[32:33], off

; DI int crow(int i, int hh) { return (i & 3) + 8 * (i >> 2) + 4 * hh; }
; template <int MODE>
; DI void attn_subtile(LDS_AS const char* Kl, LDS_AS const char* Vl, LDS_AS const char* biasl, const bf16x8 (&q)[4], AttnState& st, int kpos0, int qpos, bool need_mask, int lane) {
;     ...
;         float mx = s[0];
; #pragma unroll
;         for (int i = 1; i < 16; ++i) mx = fmaxf(mx, s[i]);
;         mx = fmaxf(mx, __shfl_xor(mx, 32));
;         const float mn = fmaxf(st.m, mx);
;         if (__any(mn > st.m)) { const float a = __builtin_amdgcn_exp2f(st.m - mn); st.o0 = st.o0 * a; st.o1 = st.o1 * a; st.l *= a; }
;         st.m = mn;
;         float ps = 0.f;
; #pragma unroll
;         for (int i = 0; i < 16; ++i) { s[i] = __builtin_amdgcn_exp2f(s[i] - mn); ps += s[i]; }
;         st.l += ps;
;     } else {
;         f32x16 lk;
; #pragma unroll
;         for (int i = 0; i < 16; ++i) {
;             const float z = s[i];
;             const float e = __builtin_amdgcn_exp2f(-fabsf(z));
;             const float sp = __builtin_amdgcn_logf(1.0f + e);
;             float lkv = -fmaxf(z, 0.f) - sp;
;             float lsv = z + lkv;
;             if (need_mask && (kpos0 + crow(i, hh) >= qpos)) { lkv = 0.f; lsv = -INFINITY; }
;             lk[i] = lkv; s[i] = lsv;
;         }
;         float tot[4], suf1[4], suf0[4];
; #pragma unroll
;         for (int g = 0; g < 4; ++g) { suf1[g] = lk[4 * g + 3] + lk[4 * g + 2]; suf0[g] = suf1[g] + lk[4 * g + 1]; tot[g] = suf0[g] + lk[4 * g]; }
;         float pb[4], cs[4];
; #pragma unroll
;         for (int g = 0; g < 4; ++g) { pb[g] = __shfl_xor(tot[g], 32); cs[g] = tot[g] + pb[g]; }
;         const float S3 = 0.f, S2 = cs[3], S1 = S2 + cs[2], S0 = S1 + cs[1], total = S0 + cs[0];
;         const float Sg[4] = {S0, S1, S2, S3};
; #pragma unroll
;         for (int g = 0; g < 4; ++g) {
;             const float base = st.l + Sg[g] + (hh == 0 ? pb[g] : 0.f);
;             s[4 * g + 3] = __builtin_amdgcn_exp2f(s[4 * g + 3] + base);
;             s[4 * g + 2] = __builtin_amdgcn_exp2f(s[4 * g + 2] + (base + lk[4 * g + 3]));
;             s[4 * g + 1] = __builtin_amdgcn_exp2f(s[4 * g + 1] + (base + suf1[g]));
;             s[4 * g + 0] = __builtin_amdgcn_exp2f(s[4 * g + 0] + (base + suf0[g]));
;         }
;         st.l += total;
;     }
;     bf16x8 pf[2];
; #pragma unroll
;     for (int s2 = 0; s2 < 2; ++s2) {
;         u32x4 w;
.Lss_b464:
	v_sub_f32_e32 v32, v32, v193
	v_exp_f32_e32 v180, v32
	v_sub_f32_e32 v32, v33, v193
	v_exp_f32_e32 v194, v32
	v_sub_f32_e32 v32, v34, v193
	v_exp_f32_e32 v195, v32
	v_sub_f32_e32 v32, v35, v193
	v_exp_f32_e32 v196, v32
	v_sub_f32_e32 v33, v36, v193
	v_add_f32_e32 v32, 0, v180
	v_exp_f32_e32 v197, v33
	v_sub_f32_e32 v33, v37, v193
	v_add_f32_e32 v32, v194, v32
	v_exp_f32_e32 v198, v33
	v_sub_f32_e32 v33, v38, v193
	v_add_f32_e32 v32, v195, v32
	v_exp_f32_e32 v199, v33
	v_sub_f32_e32 v33, v39, v193
	v_add_f32_e32 v32, v196, v32
	v_exp_f32_e32 v39, v33
	v_sub_f32_e32 v33, v40, v193
	v_add_f32_e32 v32, v197, v32
	v_exp_f32_e32 v200, v33
	v_sub_f32_e32 v33, v41, v193
	v_add_f32_e32 v32, v198, v32
	v_exp_f32_e32 v201, v33
	v_sub_f32_e32 v33, v42, v193
	v_add_f32_e32 v32, v199, v32
	v_exp_f32_e32 v202, v33
	v_sub_f32_e32 v33, v43, v193
	v_add_f32_e32 v32, v39, v32
	v_exp_f32_e32 v203, v33
	v_add_f32_e32 v32, v200, v32
	v_add_f32_e32 v32, v201, v32
	v_add_f32_e32 v32, v202, v32
	v_add_f32_e32 v146, v203, v32
	ds_read_b64_tr_b16 v[32:33], v192 offset:36864
	ds_read_b64_tr_b16 v[34:35], v192 offset:38016
	ds_read_b64_tr_b16 v[42:43], v192 offset:38080
	ds_read_b64_tr_b16 v[40:41], v192 offset:36928
	v_sub_f32_e32 v36, v44, v193
	v_exp_f32_e32 v44, v36
	v_cvt_pk_bf16_f32 v36, v180, v194
	v_cvt_pk_bf16_f32 v37, v195, v196
	v_cvt_pk_bf16_f32 v38, v197, v198
	v_cvt_pk_bf16_f32 v39, v199, v39
	v_sub_f32_e32 v47, v47, v193
	v_exp_f32_e32 v47, v47
	s_waitcnt lgkmcnt(2)
	v_mfma_f32_32x32x16_bf16 v[16:31], v[32:35], v[36:39], v[16:31]
	v_sub_f32_e32 v32, v45, v193
	v_exp_f32_e32 v45, v32
	v_sub_f32_e32 v32, v46, v193
	v_exp_f32_e32 v46, v32
	ds_read_b64_tr_b16 v[32:33], v192 offset:39168
	ds_read_b64_tr_b16 v[34:35], v192 offset:40320
	s_sub_i32 s42, s42, 32
	s_cmpk_eq_i32 s42, 0x3c0
	s_waitcnt lgkmcnt(2)
	v_mfma_f32_32x32x16_bf16 v[0:15], v[40:43], v[36:39], v[0:15]
	ds_read_b64_tr_b16 v[42:43], v192 offset:40384
	ds_read_b64_tr_b16 v[40:41], v192 offset:39232
	v_cvt_pk_bf16_f32 v36, v200, v201
	v_cvt_pk_bf16_f32 v37, v202, v203
	v_cvt_pk_bf16_f32 v38, v44, v45
	v_cvt_pk_bf16_f32 v39, v46, v47
	s_waitcnt lgkmcnt(2)
	s_nop 0
	v_mfma_f32_32x32x16_bf16 v[16:31], v[32:35], v[36:39], v[16:31]
	v_add_f32_e32 v32, v44, v146
	v_add_f32_e32 v32, v45, v32
	v_add_f32_e32 v32, v46, v32
	v_add_f32_e32 v32, v47, v32
	v_add_f32_e32 v178, v32, v178
	s_waitcnt lgkmcnt(0)
	v_mfma_f32_32x32x16_bf16 v[0:15], v[40:43], v[36:39], v[0:15]
	s_cbranch_scc1 .LBB0_466
	v_mov_b32_e32 v180, v193
	s_branch .LBB0_456

; #define QUEUE_LOOP(QI, NUNITS, BODY) \
;         for (;;) { \
;             __syncthreads(); \
;             if (tid == 0) *sunit = (int)atomicAdd(p.ctrl + cq + (QI), 1u); \
;             __syncthreads(); \
;             const int u = *sunit; \
;             if (u >= (NUNITS)) break; \
;             BODY; \
;         }
; __global__ void __launch_bounds__(512, 2) hymba_mega(Params p) {
;     ...
;         for (int ph = 0; ph < 4; ++ph) {
;             const int qi = streamer ? (ph == 0 ? 0 : ph == 1 ? 2 : ph == 2 ? 1 : 3) : (ph == 0 ? 1 : ph == 1 ? 0 : ph == 2 ? 2 : 3);
;             if (qi == 0) { QUEUE_LOOP(0, NU_SF, sample_unit<1>(p, u / NSPLIT, u % NSPLIT, smem, cq)) }
.LBB0_506:
	v_lshlrev_b32_e32 v251, 2, v138
	v_add_u32_e32 v251, 0x13000, v251
	ds_read_b32 v140, v251 offset:0
	ds_read_b32 v141, v251 offset:2048
	ds_read_b32 v142, v251 offset:4096
	ds_read_b32 v143, v251 offset:6144
	ds_read_b32 v144, v251 offset:8192
	ds_read_b32 v146, v251 offset:10240
	ds_read_b32 v168, v251 offset:12288
	ds_read_b32 v169, v251 offset:14336
	ds_read_b32 v170, v251 offset:16384
	ds_read_b32 v171, v251 offset:18432
	ds_read_b32 v172, v251 offset:20480
	ds_read_b32 v173, v251 offset:22528
	v_mov_b32_e32 v252, 0x180
	global_load_dwordx2 v[254:255], v252, s[56:57] sc0 sc1
	s_waitcnt lgkmcnt(0)
	s_branch .LBB0_401
.Lss_save:
	v_lshlrev_b32_e32 v251, 2, v138
	v_add_u32_e32 v251, 0x13000, v251
	ds_write_b32 v251, v140 offset:0
	ds_write_b32 v251, v141 offset:2048
	ds_write_b32 v251, v142 offset:4096
	ds_write_b32 v251, v143 offset:6144
	ds_write_b32 v251, v144 offset:8192
	ds_write_b32 v251, v146 offset:10240
	ds_write_b32 v251, v168 offset:12288
	ds_write_b32 v251, v169 offset:14336
	ds_write_b32 v251, v170 offset:16384
	ds_write_b32 v251, v171 offset:18432
	ds_write_b32 v251, v172 offset:20480
	ds_write_b32 v251, v173 offset:22528
	s_waitcnt lgkmcnt(0)
	s_branch .LBB0_441
